# global attention units: hand-written software-pipelined loop with LDS-DMA K/V staging (ring of 4/3 buffers)
# speedup vs baseline: 1.0172x; 1.0172x over previous
; #define ATT_LAS __attribute__((address_space(3)))
; #define ATT_LDK(dst, buf) do { _Pragma("unroll") for (int d0_ = 0; d0_ < 4; ++d0_) { dst[2 * d0_] = *(const ATT_LAS bf16x8*)((buf) + kfrag + d0_ * 2048); dst[2 * d0_ + 1] = *(const ATT_LAS bf16x8*)((buf) + kfrag + d0_ * 2048 + 512); } } while (0)
; template <bool NOMAX> ...
;         const f32x16 zero16 = {};
;         u32x4 kreg, vreg; bf16x8 kf[8]; f32x16 c0, c1, e0, e1;
;         { const u32x4 k0 = *(const u32x4*)(kg + (size_t)ATT_TROW(0) * PITCH), k1 = *(const u32x4*)(kg + (size_t)ATT_TROW(1) * PITCH);
;           *(ATT_LAS u32x4*)(ATT_KBUF(0) + koff) = k0; *(ATT_LAS u32x4*)(ATT_KBUF(1) + koff) = k1; }
;         __syncthreads();
;         kreg = *(const u32x4*)(kg + (size_t)ATT_TROW(2) * PITCH); vreg = *(const u32x4*)(vg + (size_t)ATT_TROW(0) * PITCH);
;         ATT_LDK(kf, ATT_KBUF(0));
;         c0 = (f32x16){}; c1 = (f32x16){};
; #pragma unroll
;         for (int d0 = 0; d0 < 4; ++d0) { c0 = __builtin_amdgcn_mfma_f32_32x32x16_bf16(kf[2 * d0], qf[d0], c0, 0, 0, 0); c1 = __builtin_amdgcn_mfma_f32_32x32x16_bf16(kf[2 * d0 + 1], qf[d0], c1, 0, 0, 0); }
;         m = NOMAX ? 0.f : rowmax32(c0, c1);
; #pragma unroll
;         for (int r = 0; r < 16; ++r) { e0[r] = __builtin_amdgcn_exp2f(c0[r] - m); e1[r] = __builtin_amdgcn_exp2f(c1[r] - m); }
;         ATT_LDK(kf, ATT_KBUF(1));
;         *(ATT_LAS u32x4*)(ATT_KBUF(2) + koff) = kreg; *(ATT_LAS u32x4*)(ATT_VBUF(0) + voff) = vreg;
;         __syncthreads();
;         u32x4 kregB = kreg, vregB = vreg;
;         kreg = *(const u32x4*)(kg + (size_t)ATT_TROW(3) * PITCH); vreg = *(const u32x4*)(vg + (size_t)ATT_TROW(1) * PITCH);
;         int kb2 = 0;
.LBB0_644:
	s_xor_b64 s[2:3], s[24:25], -1
	s_cmp_gt_i32 s71, 0
	s_cselect_b64 s[0:1], -1, 0
	s_and_b64 s[0:1], s[4:5], s[0:1]
	s_andn2_b64 vcc, exec, s[0:1]
	s_waitcnt lgkmcnt(0)
	s_cbranch_vccnz .LBB0_536
	s_branch .Lmk_entry
.Lmk_entry_g:
	v_mov_b32_e32 v202, 0
	v_mov_b32_e32 v124, 0
	v_mov_b32_e32 v204, 0
	v_mov_b32_e32 v205, 0
	v_mov_b32_e32 v208, 0
	v_mov_b32_e32 v209, 0
	v_mov_b32_e32 v0, 0
	v_mov_b32_e32 v1, 0
	v_mov_b32_e32 v2, 0
	v_mov_b32_e32 v3, 0
	v_mov_b32_e32 v4, 0
	v_mov_b32_e32 v5, 0
	v_mov_b32_e32 v6, 0
	v_mov_b32_e32 v7, 0
	v_mov_b32_e32 v8, 0
	v_mov_b32_e32 v9, 0
	v_mov_b32_e32 v10, 0
	v_mov_b32_e32 v11, 0
	v_mov_b32_e32 v12, 0
	v_mov_b32_e32 v13, 0
	v_mov_b32_e32 v14, 0
	v_mov_b32_e32 v15, 0
	v_mov_b32_e32 v16, 0
	v_mov_b32_e32 v17, 0
	v_mov_b32_e32 v18, 0
	v_mov_b32_e32 v19, 0
	v_mov_b32_e32 v20, 0
	v_mov_b32_e32 v21, 0
	v_mov_b32_e32 v22, 0
	v_mov_b32_e32 v23, 0
	v_mov_b32_e32 v24, 0
	v_mov_b32_e32 v25, 0
	v_mov_b32_e32 v26, 0
	v_mov_b32_e32 v27, 0
	v_mov_b32_e32 v28, 0
	v_mov_b32_e32 v29, 0
	v_mov_b32_e32 v30, 0
	v_mov_b32_e32 v31, 0
	s_lshl_b32 s92, s93, 6
	s_add_i32 s84, s27, s92
	v_lshrrev_b32_e32 v116, 6, v192
	v_and_b32_e32 v117, 63, v192
	v_lshrrev_b32_e32 v118, 3, v117
	v_sub_u32_e32 v118, v118, v116
	v_mul_i32_i24_e32 v248, 0x8ff0, v118
	v_and_b32_e32 v118, 3, v116
	v_lshlrev_b32_e32 v118, 4, v118
	v_lshlrev_b32_e32 v119, 3, v116
	v_sub_u32_e32 v118, v118, v119
	v_bfe_u32 v119, v117, 3, 1
	v_bfe_u32 v242, v117, 4, 1
	v_bfe_u32 v243, v117, 5, 1
	v_add_u32_e32 v242, v119, v242
	v_lshl_add_u32 v242, v243, 1, v242
	v_lshl_add_u32 v118, v242, 1, v118
	v_lshrrev_b32_e32 v243, 2, v116
	v_sub_u32_e32 v243, v243, v119
	v_mul_i32_i24_e32 v118, 0x1200, v118
	v_lshl_add_u32 v249, v243, 6, v118
	v_readfirstlane_b32 s100, v116
	s_mov_b64 s[98:99], 0x48000
	s_lshl_b32 s100, s100, 10
	v_add_u32_e32 v253, s35, v231
	v_mad_i64_i32 v[244:245], s[80:81], s30, v215, v[198:199]
	v_ashrrev_i32_e32 v243, 31, v248
	v_mov_b32_e32 v242, v248
	v_lshl_add_u64 v[244:245], v[242:243], 0, v[244:245]
	v_mad_i64_i32 v[246:247], s[80:81], s30, v215, v[200:201]
	v_ashrrev_i32_e32 v243, 31, v249
	v_mov_b32_e32 v242, v249
	v_lshl_add_u64 v[246:247], v[242:243], 0, v[246:247]
	s_add_i32 s71, s71, 4
	s_add_i32 s81, s100, 0x0
	s_mov_b32 m0, s81
	s_nop 0
	global_load_lds_dwordx4 v[244:245], off
	v_lshl_add_u64 v[244:245], v[244:245], 0, s[98:99]
	s_add_i32 s81, s100, 0x2000
	s_mov_b32 m0, s81
	s_nop 0
	global_load_lds_dwordx4 v[244:245], off
	v_lshl_add_u64 v[244:245], v[244:245], 0, s[98:99]
	s_add_i32 s81, s100, 0x4000
	s_mov_b32 m0, s81
	s_nop 0
	global_load_lds_dwordx4 v[244:245], off
	v_lshl_add_u64 v[244:245], v[244:245], 0, s[98:99]
	s_add_i32 s81, s100, 0x6000
	s_mov_b32 m0, s81
	s_nop 0
	global_load_lds_dwordx4 v[246:247], off
	v_lshl_add_u64 v[246:247], v[246:247], 0, s[98:99]
	s_waitcnt vmcnt(0)
	s_waitcnt lgkmcnt(0)
	s_barrier
	s_add_i32 s81, s100, 0xe000
	s_mov_b32 m0, s81
	s_nop 0
	global_load_lds_dwordx4 v[244:245], off
	v_lshl_add_u64 v[244:245], v[244:245], 0, s[98:99]
	s_add_i32 s81, s100, 0x8000
	s_mov_b32 m0, s81
	s_nop 0
	global_load_lds_dwordx4 v[246:247], off
	v_lshl_add_u64 v[246:247], v[246:247], 0, s[98:99]
	v_mov_b32_e32 v243, v221
	ds_read_b128 v[128:131], v243
	ds_read_b128 v[132:135], v243 offset:512
	ds_read_b128 v[136:139], v243 offset:2048
	ds_read_b128 v[140:143], v243 offset:2560
	ds_read_b128 v[144:147], v243 offset:4096
	ds_read_b128 v[148:151], v243 offset:4608
	ds_read_b128 v[152:155], v243 offset:6144
	ds_read_b128 v[156:159], v243 offset:6656
	s_waitcnt lgkmcnt(7)
	v_mfma_f32_32x32x16_bf16 v[32:47], v[128:131], v[96:99], 0
	s_waitcnt lgkmcnt(6)
	v_mfma_f32_32x32x16_bf16 v[64:79], v[132:135], v[96:99], 0
	s_waitcnt lgkmcnt(5)
	v_mfma_f32_32x32x16_bf16 v[32:47], v[136:139], v[100:103], v[32:47]
	s_waitcnt lgkmcnt(4)
	v_mfma_f32_32x32x16_bf16 v[64:79], v[140:143], v[100:103], v[64:79]
	s_waitcnt lgkmcnt(3)
	v_mfma_f32_32x32x16_bf16 v[32:47], v[144:147], v[104:107], v[32:47]
	s_waitcnt lgkmcnt(2)
	v_mfma_f32_32x32x16_bf16 v[64:79], v[148:151], v[104:107], v[64:79]
	s_waitcnt lgkmcnt(1)
	v_mfma_f32_32x32x16_bf16 v[32:47], v[152:155], v[108:111], v[32:47]
	s_waitcnt lgkmcnt(0)
	v_mfma_f32_32x32x16_bf16 v[64:79], v[156:159], v[108:111], v[64:79]
	v_add_u32_e32 v243, 0x2000, v221
	ds_read_b128 v[128:131], v243
	ds_read_b128 v[132:135], v243 offset:512
	ds_read_b128 v[136:139], v243 offset:2048
	ds_read_b128 v[140:143], v243 offset:2560
	ds_read_b128 v[144:147], v243 offset:4096
	ds_read_b128 v[148:151], v243 offset:4608
	ds_read_b128 v[152:155], v243 offset:6144
	ds_read_b128 v[156:159], v243 offset:6656
	s_nop 2
	v_exp_f32_e32 v32, v32
	v_exp_f32_e32 v33, v33
	v_exp_f32_e32 v34, v34
	v_exp_f32_e32 v35, v35
	v_exp_f32_e32 v36, v36
	v_exp_f32_e32 v37, v37
	v_exp_f32_e32 v38, v38
	v_exp_f32_e32 v39, v39
	v_exp_f32_e32 v40, v40
	v_exp_f32_e32 v41, v41
	v_exp_f32_e32 v42, v42
	v_exp_f32_e32 v43, v43
	v_exp_f32_e32 v44, v44
	v_exp_f32_e32 v45, v45
	v_exp_f32_e32 v46, v46
	v_exp_f32_e32 v47, v47
	v_exp_f32_e32 v64, v64
	v_exp_f32_e32 v65, v65
	v_exp_f32_e32 v66, v66
	v_exp_f32_e32 v67, v67
	v_exp_f32_e32 v68, v68
	v_exp_f32_e32 v69, v69
	v_exp_f32_e32 v70, v70
	v_exp_f32_e32 v71, v71
	v_exp_f32_e32 v72, v72
	v_exp_f32_e32 v73, v73
	v_exp_f32_e32 v74, v74
	v_exp_f32_e32 v75, v75
	v_exp_f32_e32 v76, v76
	v_exp_f32_e32 v77, v77
	v_exp_f32_e32 v78, v78
	v_exp_f32_e32 v79, v79
	s_waitcnt lgkmcnt(0)
	s_barrier
	s_mov_b32 s7, 1
.Lg_loop:
	s_add_i32 s96, s7, 3
	s_cmp_lt_i32 s96, s71
	s_cselect_b64 s[82:83], -1, 0
	s_cbranch_scc0 .Lgo_nk
	s_cmp_lg_u32 s96, 4
	s_cbranch_scc1 .Lgo_ks
	v_mad_i64_i32 v[244:245], s[80:81], s84, v215, v[198:199]
	v_ashrrev_i32_e32 v243, 31, v248
	v_mov_b32_e32 v242, v248
	v_lshl_add_u64 v[244:245], v[242:243], 0, v[244:245]
.Lgo_ks:
	s_and_b32 s80, s96, 3
	s_lshl_b32 s81, s80, 13
	s_cmp_eq_u32 s80, 3
	s_cselect_b32 s81, 0xe000, s81
	s_add_i32 s81, s81, s100
	s_mov_b32 m0, s81
	s_nop 0
	global_load_lds_dwordx4 v[244:245], off
	v_lshl_add_u64 v[244:245], v[244:245], 0, s[98:99]
.Lgo_nk:
	s_add_i32 s96, s7, 1
	s_cmp_lt_i32 s96, s71
	s_cbranch_scc0 .Lgo_nv
	s_cmp_lg_u32 s96, 4
	s_cbranch_scc1 .Lgo_vs
	v_mad_i64_i32 v[246:247], s[80:81], s84, v215, v[200:201]
	v_ashrrev_i32_e32 v243, 31, v249
	v_mov_b32_e32 v242, v249
	v_lshl_add_u64 v[246:247], v[242:243], 0, v[246:247]
.Lgo_vs:
	s_mul_hi_u32 s80, s96, 0x55555556
	s_mul_i32 s80, s80, 3
	s_sub_u32 s80, s96, s80
	s_lshl_b32 s81, s80, 13
	s_cmp_eq_u32 s80, 2
	s_cselect_b32 s81, 0x6000, s81
	s_add_i32 s81, s81, 0x6000
	s_add_i32 s81, s81, s100
	s_mov_b32 m0, s81
	s_nop 0
	global_load_lds_dwordx4 v[246:247], off
	v_lshl_add_u64 v[246:247], v[246:247], 0, s[98:99]
.Lgo_nv:
	s_add_i32 s72, s7, 2
	s_mul_hi_u32 s80, s72, 0x55555556
	s_mul_i32 s80, s80, 3
	s_sub_u32 s80, s72, s80
	s_lshl_b32 s81, s80, 13
	s_cmp_eq_u32 s80, 2
	s_cselect_b32 s81, 0x6000, s81
	v_add_u32_e32 v242, s81, v253
	s_add_i32 s72, s7, 1
	s_and_b32 s80, s72, 3
	s_lshl_b32 s81, s80, 13
	s_cmp_eq_u32 s80, 3
	s_cselect_b32 s81, 0xe000, s81
	v_add_u32_e32 v243, s81, v221
	ds_read_b64_tr_b16 v[160:161], v242 offset:24576
	ds_read_b64_tr_b16 v[162:163], v242 offset:25088
	ds_read_b64_tr_b16 v[164:165], v242 offset:25600
	ds_read_b64_tr_b16 v[166:167], v242 offset:26112
	ds_read_b64_tr_b16 v[168:169], v242 offset:26624
	ds_read_b64_tr_b16 v[170:171], v242 offset:27136
	ds_read_b64_tr_b16 v[172:173], v242 offset:27648
	ds_read_b64_tr_b16 v[174:175], v242 offset:28160
	v_mfma_f32_32x32x16_bf16 v[80:95], v[128:131], v[96:99], 0
	v_add_f32_e32 v204, v204, v32
	v_add_f32_e32 v205, v205, v33
	v_add_f32_e32 v208, v208, v34
	v_add_f32_e32 v209, v209, v35
	v_cvt_pk_bf16_f32 v112, v32, v33
	v_cvt_pk_bf16_f32 v113, v34, v35
	v_mfma_f32_32x32x16_bf16 v[48:63], v[132:135], v[96:99], 0
	v_add_f32_e32 v204, v204, v36
	v_add_f32_e32 v205, v205, v37
	v_add_f32_e32 v208, v208, v38
	v_add_f32_e32 v209, v209, v39
	v_cvt_pk_bf16_f32 v114, v36, v37
	v_cvt_pk_bf16_f32 v115, v38, v39
	v_mfma_f32_32x32x16_bf16 v[80:95], v[136:139], v[100:103], v[80:95]
	v_add_f32_e32 v204, v204, v40
	v_add_f32_e32 v205, v205, v41
	v_add_f32_e32 v208, v208, v42
	v_add_f32_e32 v209, v209, v43
	v_cvt_pk_bf16_f32 v116, v40, v41
	v_cvt_pk_bf16_f32 v117, v42, v43
	v_mfma_f32_32x32x16_bf16 v[48:63], v[140:143], v[100:103], v[48:63]
	v_add_f32_e32 v204, v204, v44
	v_add_f32_e32 v205, v205, v45
	v_add_f32_e32 v208, v208, v46
	v_add_f32_e32 v209, v209, v47
	v_cvt_pk_bf16_f32 v118, v44, v45
	v_cvt_pk_bf16_f32 v119, v46, v47
	v_mfma_f32_32x32x16_bf16 v[80:95], v[144:147], v[104:107], v[80:95]
	v_add_f32_e32 v204, v204, v64
	v_add_f32_e32 v205, v205, v65
	v_add_f32_e32 v208, v208, v66
	v_add_f32_e32 v209, v209, v67
	v_cvt_pk_bf16_f32 v120, v64, v65
	v_cvt_pk_bf16_f32 v121, v66, v67
	v_mfma_f32_32x32x16_bf16 v[48:63], v[148:151], v[104:107], v[48:63]
	v_add_f32_e32 v204, v204, v68
	v_add_f32_e32 v205, v205, v69
	v_add_f32_e32 v208, v208, v70
	v_add_f32_e32 v209, v209, v71
	v_cvt_pk_bf16_f32 v122, v68, v69
	v_cvt_pk_bf16_f32 v123, v70, v71
	v_mfma_f32_32x32x16_bf16 v[80:95], v[152:155], v[108:111], v[80:95]
	v_add_f32_e32 v204, v204, v72
	v_add_f32_e32 v205, v205, v73
	v_add_f32_e32 v208, v208, v74
	v_add_f32_e32 v209, v209, v75
	v_cvt_pk_bf16_f32 v124, v72, v73
	v_cvt_pk_bf16_f32 v125, v74, v75
	v_mfma_f32_32x32x16_bf16 v[48:63], v[156:159], v[108:111], v[48:63]
	v_add_f32_e32 v204, v204, v76
	v_add_f32_e32 v205, v205, v77
	v_add_f32_e32 v208, v208, v78
	v_add_f32_e32 v209, v209, v79
	v_cvt_pk_bf16_f32 v126, v76, v77
	v_cvt_pk_bf16_f32 v127, v78, v79
	ds_read_b64_tr_b16 v[176:177], v242 offset:28672
	ds_read_b64_tr_b16 v[178:179], v242 offset:29184
	ds_read_b64_tr_b16 v[180:181], v242 offset:29696
	ds_read_b64_tr_b16 v[182:183], v242 offset:30208
	ds_read_b64_tr_b16 v[184:185], v242 offset:30720
	ds_read_b64_tr_b16 v[186:187], v242 offset:31232
	ds_read_b64_tr_b16 v[188:189], v242 offset:31744
	s_waitcnt lgkmcnt(14)
	ds_read_b64_tr_b16 v[190:191], v242 offset:32256
	s_waitcnt lgkmcnt(14)
	v_mfma_f32_32x32x16_bf16 v[0:15], v[160:163], v[112:115], v[0:15]
	v_exp_f32_e32 v80, v80
	v_exp_f32_e32 v81, v81
	v_exp_f32_e32 v82, v82
	v_exp_f32_e32 v83, v83
	s_waitcnt lgkmcnt(12)
	v_mfma_f32_32x32x16_bf16 v[0:15], v[164:167], v[116:119], v[0:15]
	v_exp_f32_e32 v84, v84
	v_exp_f32_e32 v85, v85
	v_exp_f32_e32 v86, v86
	v_exp_f32_e32 v87, v87
	s_waitcnt lgkmcnt(10)
	v_mfma_f32_32x32x16_bf16 v[0:15], v[168:171], v[120:123], v[0:15]
	v_exp_f32_e32 v88, v88
	v_exp_f32_e32 v89, v89
	v_exp_f32_e32 v90, v90
	v_exp_f32_e32 v91, v91
	ds_read_b128 v[128:131], v243
	ds_read_b128 v[132:135], v243 offset:512
	s_waitcnt lgkmcnt(10)
	v_mfma_f32_32x32x16_bf16 v[0:15], v[172:175], v[124:127], v[0:15]
	v_exp_f32_e32 v92, v92
	v_exp_f32_e32 v93, v93
	v_exp_f32_e32 v94, v94
	v_exp_f32_e32 v95, v95
	ds_read_b128 v[136:139], v243 offset:2048
	ds_read_b128 v[140:143], v243 offset:2560
	s_waitcnt lgkmcnt(10)
	v_mfma_f32_32x32x16_bf16 v[16:31], v[176:179], v[112:115], v[16:31]
	v_exp_f32_e32 v48, v48
	v_exp_f32_e32 v49, v49
	v_exp_f32_e32 v50, v50
	v_exp_f32_e32 v51, v51
	ds_read_b128 v[144:147], v243 offset:4096
	ds_read_b128 v[148:151], v243 offset:4608
	s_waitcnt lgkmcnt(10)
	v_mfma_f32_32x32x16_bf16 v[16:31], v[180:183], v[116:119], v[16:31]
	v_exp_f32_e32 v52, v52
	v_exp_f32_e32 v53, v53
	v_exp_f32_e32 v54, v54
	v_exp_f32_e32 v55, v55
	ds_read_b128 v[152:155], v243 offset:6144
	ds_read_b128 v[156:159], v243 offset:6656
	s_waitcnt lgkmcnt(10)
	v_mfma_f32_32x32x16_bf16 v[16:31], v[184:187], v[120:123], v[16:31]
	v_exp_f32_e32 v56, v56
	v_exp_f32_e32 v57, v57
	v_exp_f32_e32 v58, v58
	v_exp_f32_e32 v59, v59
	s_waitcnt lgkmcnt(8)
	v_mfma_f32_32x32x16_bf16 v[16:31], v[188:191], v[124:127], v[16:31]
	v_exp_f32_e32 v60, v60
	v_exp_f32_e32 v61, v61
	v_exp_f32_e32 v62, v62
	v_exp_f32_e32 v63, v63
	s_waitcnt lgkmcnt(0)
	s_and_b64 vcc, exec, s[82:83]
	s_cbranch_vccz .Lgo_w0
	s_waitcnt vmcnt(2)
	s_branch .Lgo_w1

; template <bool NOMAX> ...
;     ...
;         for (int t = 1; t < NF; t += 2) {
;             ATT_STEP(t, kreg, vreg, kregB, vregB, e0, e1, c0, c1);
;             if (t + 1 < NF) ATT_STEP(t + 1, kregB, vregB, kreg, vreg, c0, c1, e0, e1);
.Lgo_w1:
	s_barrier
	s_add_i32 s7, s7, 1
	s_cmp_ge_i32 s7, s71
	s_cbranch_scc1 .Lg_drainB
	s_add_i32 s96, s7, 3
	s_cmp_lt_i32 s96, s71
	s_cselect_b64 s[82:83], -1, 0
	s_cbranch_scc0 .Lge_nk
	s_cmp_lg_u32 s96, 4
	s_cbranch_scc1 .Lge_ks
	v_mad_i64_i32 v[244:245], s[80:81], s84, v215, v[198:199]
	v_ashrrev_i32_e32 v243, 31, v248
	v_mov_b32_e32 v242, v248
	v_lshl_add_u64 v[244:245], v[242:243], 0, v[244:245]

; template <bool NOMAX> ...
;     ...
;         for (int t = 1; t < NF; t += 2) {
;             ATT_STEP(t, kreg, vreg, kregB, vregB, e0, e1, c0, c1);
;             if (t + 1 < NF) ATT_STEP(t + 1, kregB, vregB, kreg, vreg, c0, c1, e0, e1);
.Lge_nv:
	s_add_i32 s72, s7, 2
	s_mul_hi_u32 s80, s72, 0x55555556
	s_mul_i32 s80, s80, 3
	s_sub_u32 s80, s72, s80
	s_lshl_b32 s81, s80, 13
	s_cmp_eq_u32 s80, 2
	s_cselect_b32 s81, 0x6000, s81
	v_add_u32_e32 v242, s81, v253
	s_add_i32 s72, s7, 1
	s_and_b32 s80, s72, 3
	s_lshl_b32 s81, s80, 13
	s_cmp_eq_u32 s80, 3
	s_cselect_b32 s81, 0xe000, s81
	v_add_u32_e32 v243, s81, v221
	ds_read_b64_tr_b16 v[160:161], v242 offset:24576
	ds_read_b64_tr_b16 v[162:163], v242 offset:25088
	ds_read_b64_tr_b16 v[164:165], v242 offset:25600
	ds_read_b64_tr_b16 v[166:167], v242 offset:26112
	ds_read_b64_tr_b16 v[168:169], v242 offset:26624
	ds_read_b64_tr_b16 v[170:171], v242 offset:27136
	ds_read_b64_tr_b16 v[172:173], v242 offset:27648
	ds_read_b64_tr_b16 v[174:175], v242 offset:28160
	v_mfma_f32_32x32x16_bf16 v[32:47], v[128:131], v[96:99], 0
	v_add_f32_e32 v204, v204, v80
	v_add_f32_e32 v205, v205, v81
	v_add_f32_e32 v208, v208, v82
	v_add_f32_e32 v209, v209, v83
	v_cvt_pk_bf16_f32 v112, v80, v81
	v_cvt_pk_bf16_f32 v113, v82, v83
	v_mfma_f32_32x32x16_bf16 v[64:79], v[132:135], v[96:99], 0
	v_add_f32_e32 v204, v204, v84
	v_add_f32_e32 v205, v205, v85
	v_add_f32_e32 v208, v208, v86
	v_add_f32_e32 v209, v209, v87
	v_cvt_pk_bf16_f32 v114, v84, v85
	v_cvt_pk_bf16_f32 v115, v86, v87
	v_mfma_f32_32x32x16_bf16 v[32:47], v[136:139], v[100:103], v[32:47]
	v_add_f32_e32 v204, v204, v88
	v_add_f32_e32 v205, v205, v89
	v_add_f32_e32 v208, v208, v90
	v_add_f32_e32 v209, v209, v91
	v_cvt_pk_bf16_f32 v116, v88, v89
	v_cvt_pk_bf16_f32 v117, v90, v91
	v_mfma_f32_32x32x16_bf16 v[64:79], v[140:143], v[100:103], v[64:79]
	v_add_f32_e32 v204, v204, v92
	v_add_f32_e32 v205, v205, v93
	v_add_f32_e32 v208, v208, v94
	v_add_f32_e32 v209, v209, v95
	v_cvt_pk_bf16_f32 v118, v92, v93
	v_cvt_pk_bf16_f32 v119, v94, v95
	v_mfma_f32_32x32x16_bf16 v[32:47], v[144:147], v[104:107], v[32:47]
	v_add_f32_e32 v204, v204, v48
	v_add_f32_e32 v205, v205, v49
	v_add_f32_e32 v208, v208, v50
	v_add_f32_e32 v209, v209, v51
	v_cvt_pk_bf16_f32 v120, v48, v49
	v_cvt_pk_bf16_f32 v121, v50, v51
	v_mfma_f32_32x32x16_bf16 v[64:79], v[148:151], v[104:107], v[64:79]
	v_add_f32_e32 v204, v204, v52
	v_add_f32_e32 v205, v205, v53
	v_add_f32_e32 v208, v208, v54
	v_add_f32_e32 v209, v209, v55
	v_cvt_pk_bf16_f32 v122, v52, v53
	v_cvt_pk_bf16_f32 v123, v54, v55
	v_mfma_f32_32x32x16_bf16 v[32:47], v[152:155], v[108:111], v[32:47]
	v_add_f32_e32 v204, v204, v56
	v_add_f32_e32 v205, v205, v57
	v_add_f32_e32 v208, v208, v58
	v_add_f32_e32 v209, v209, v59
	v_cvt_pk_bf16_f32 v124, v56, v57
	v_cvt_pk_bf16_f32 v125, v58, v59
	v_mfma_f32_32x32x16_bf16 v[64:79], v[156:159], v[108:111], v[64:79]
	v_add_f32_e32 v204, v204, v60
	v_add_f32_e32 v205, v205, v61
	v_add_f32_e32 v208, v208, v62
	v_add_f32_e32 v209, v209, v63
	v_cvt_pk_bf16_f32 v126, v60, v61
	v_cvt_pk_bf16_f32 v127, v62, v63
	ds_read_b64_tr_b16 v[176:177], v242 offset:28672
	ds_read_b64_tr_b16 v[178:179], v242 offset:29184
	ds_read_b64_tr_b16 v[180:181], v242 offset:29696
	ds_read_b64_tr_b16 v[182:183], v242 offset:30208
	ds_read_b64_tr_b16 v[184:185], v242 offset:30720
	ds_read_b64_tr_b16 v[186:187], v242 offset:31232
	ds_read_b64_tr_b16 v[188:189], v242 offset:31744
	s_waitcnt lgkmcnt(14)
	ds_read_b64_tr_b16 v[190:191], v242 offset:32256
	s_waitcnt lgkmcnt(14)
	v_mfma_f32_32x32x16_bf16 v[0:15], v[160:163], v[112:115], v[0:15]
	v_exp_f32_e32 v32, v32
	v_exp_f32_e32 v33, v33
	v_exp_f32_e32 v34, v34
	v_exp_f32_e32 v35, v35
	s_waitcnt lgkmcnt(12)
	v_mfma_f32_32x32x16_bf16 v[0:15], v[164:167], v[116:119], v[0:15]
	v_exp_f32_e32 v36, v36
	v_exp_f32_e32 v37, v37
	v_exp_f32_e32 v38, v38
	v_exp_f32_e32 v39, v39
	s_waitcnt lgkmcnt(10)
	v_mfma_f32_32x32x16_bf16 v[0:15], v[168:171], v[120:123], v[0:15]
	v_exp_f32_e32 v40, v40
	v_exp_f32_e32 v41, v41
	v_exp_f32_e32 v42, v42
	v_exp_f32_e32 v43, v43
	ds_read_b128 v[128:131], v243
	ds_read_b128 v[132:135], v243 offset:512
	s_waitcnt lgkmcnt(10)
	v_mfma_f32_32x32x16_bf16 v[0:15], v[172:175], v[124:127], v[0:15]
	v_exp_f32_e32 v44, v44
	v_exp_f32_e32 v45, v45
	v_exp_f32_e32 v46, v46
	v_exp_f32_e32 v47, v47
	ds_read_b128 v[136:139], v243 offset:2048
	ds_read_b128 v[140:143], v243 offset:2560
	s_waitcnt lgkmcnt(10)
	v_mfma_f32_32x32x16_bf16 v[16:31], v[176:179], v[112:115], v[16:31]
	v_exp_f32_e32 v64, v64
	v_exp_f32_e32 v65, v65
	v_exp_f32_e32 v66, v66
	v_exp_f32_e32 v67, v67
	ds_read_b128 v[144:147], v243 offset:4096
	ds_read_b128 v[148:151], v243 offset:4608
	s_waitcnt lgkmcnt(10)
	v_mfma_f32_32x32x16_bf16 v[16:31], v[180:183], v[116:119], v[16:31]
	v_exp_f32_e32 v68, v68
	v_exp_f32_e32 v69, v69
	v_exp_f32_e32 v70, v70
	v_exp_f32_e32 v71, v71
	ds_read_b128 v[152:155], v243 offset:6144
	ds_read_b128 v[156:159], v243 offset:6656
	s_waitcnt lgkmcnt(10)
	v_mfma_f32_32x32x16_bf16 v[16:31], v[184:187], v[120:123], v[16:31]
	v_exp_f32_e32 v72, v72
	v_exp_f32_e32 v73, v73
	v_exp_f32_e32 v74, v74
	v_exp_f32_e32 v75, v75
	s_waitcnt lgkmcnt(8)
	v_mfma_f32_32x32x16_bf16 v[16:31], v[188:191], v[124:127], v[16:31]
	v_exp_f32_e32 v76, v76
	v_exp_f32_e32 v77, v77
	v_exp_f32_e32 v78, v78
	v_exp_f32_e32 v79, v79
	s_waitcnt lgkmcnt(0)
	s_and_b64 vcc, exec, s[82:83]
	s_cbranch_vccz .Lge_w0
	s_waitcnt vmcnt(2)
	s_branch .Lge_w1

; #define ATT_LAS __attribute__((address_space(3)))
; __device__ __forceinline__ unsigned pk_bf16(float lo, float hi) { unsigned r; asm volatile("v_cvt_pk_bf16_f32 %0, %1, %2" : "=v"(r) : "v"(lo), "v"(hi)); return r; }
; template <bool NOMAX> ...
;     ...
;         if ((NF - 1) & 1) { e0 = c0; e1 = c1; }
;     ...
;         { u32x4 pw[4]; float sacc = 0.f;
; #pragma unroll
;           for (int r = 0; r < 16; ++r) sacc += e0[r] + e1[r];
;           lsum += sacc;
; #pragma unroll
;           for (int j = 0; j < 4; ++j) { pw[0][j] = pk_bf16(e0[2 * j], e0[2 * j + 1]); pw[1][j] = pk_bf16(e0[8 + 2 * j], e0[8 + 2 * j + 1]);
;                                         pw[2][j] = pk_bf16(e1[2 * j], e1[2 * j + 1]); pw[3][j] = pk_bf16(e1[8 + 2 * j], e1[8 + 2 * j + 1]); }
;           const ATT_LAS unsigned char* vb = ATT_VBUF((NF - 1) & 1) + vlane;
; #pragma unroll
;           for (int s = 0; s < 4; ++s) { const bf16x8 pa = __builtin_bit_cast(bf16x8, pw[s]);
;               { const s16x4 lo = vtr(vb + s * 1024), h4 = vtr(vb + s * 1024 + 512); const bf16x8 vf = (bf16x8){lo[0], lo[1], lo[2], lo[3], h4[0], h4[1], h4[2], h4[3]};
;                 o0 = __builtin_amdgcn_mfma_f32_32x32x16_bf16(vf, pa, o0, 0, 0, 0); }
;               { const s16x4 lo = vtr(vb + 4096 + s * 1024), h4 = vtr(vb + 4096 + s * 1024 + 512); const bf16x8 vf = (bf16x8){lo[0], lo[1], lo[2], lo[3], h4[0], h4[1], h4[2], h4[3]};
;                 o1 = __builtin_amdgcn_mfma_f32_32x32x16_bf16(vf, pa, o1, 0, 0, 0); } }
;         }
;         __syncthreads();
.Lge_w1:
	s_barrier
	s_add_i32 s7, s7, 1
	s_cmp_lt_i32 s7, s71
	s_cbranch_scc1 .Lg_loop
	s_add_i32 s72, s7, 2
	s_mul_hi_u32 s80, s72, 0x55555556
	s_mul_i32 s80, s80, 3
	s_sub_u32 s80, s72, s80
	s_lshl_b32 s81, s80, 13
	s_cmp_eq_u32 s80, 2
	s_cselect_b32 s81, 0x6000, s81
	v_add_u32_e32 v242, s81, v253
	ds_read_b64_tr_b16 v[160:161], v242 offset:24576
	ds_read_b64_tr_b16 v[162:163], v242 offset:25088
	ds_read_b64_tr_b16 v[164:165], v242 offset:25600
	ds_read_b64_tr_b16 v[166:167], v242 offset:26112
	ds_read_b64_tr_b16 v[168:169], v242 offset:26624
	ds_read_b64_tr_b16 v[170:171], v242 offset:27136
	ds_read_b64_tr_b16 v[172:173], v242 offset:27648
	ds_read_b64_tr_b16 v[174:175], v242 offset:28160
	v_add_f32_e32 v204, v204, v32
	v_add_f32_e32 v205, v205, v33
	v_add_f32_e32 v208, v208, v34
	v_add_f32_e32 v209, v209, v35
	v_add_f32_e32 v204, v204, v36
	v_add_f32_e32 v205, v205, v37
	v_add_f32_e32 v208, v208, v38
	v_add_f32_e32 v209, v209, v39
	v_add_f32_e32 v204, v204, v40
	v_add_f32_e32 v205, v205, v41
	v_add_f32_e32 v208, v208, v42
	v_add_f32_e32 v209, v209, v43
	v_add_f32_e32 v204, v204, v44
	v_add_f32_e32 v205, v205, v45
	v_add_f32_e32 v208, v208, v46
	v_add_f32_e32 v209, v209, v47
	v_add_f32_e32 v204, v204, v64
	v_add_f32_e32 v205, v205, v65
	v_add_f32_e32 v208, v208, v66
	v_add_f32_e32 v209, v209, v67
	v_add_f32_e32 v204, v204, v68
	v_add_f32_e32 v205, v205, v69
	v_add_f32_e32 v208, v208, v70
	v_add_f32_e32 v209, v209, v71
	v_add_f32_e32 v204, v204, v72
	v_add_f32_e32 v205, v205, v73
	v_add_f32_e32 v208, v208, v74
	v_add_f32_e32 v209, v209, v75
	v_add_f32_e32 v204, v204, v76
	v_add_f32_e32 v205, v205, v77
	v_add_f32_e32 v208, v208, v78
	v_add_f32_e32 v209, v209, v79
	v_cvt_pk_bf16_f32 v112, v32, v33
	v_cvt_pk_bf16_f32 v113, v34, v35
	v_cvt_pk_bf16_f32 v114, v36, v37
	v_cvt_pk_bf16_f32 v115, v38, v39
	v_cvt_pk_bf16_f32 v116, v40, v41
	v_cvt_pk_bf16_f32 v117, v42, v43
	v_cvt_pk_bf16_f32 v118, v44, v45
	v_cvt_pk_bf16_f32 v119, v46, v47
	v_cvt_pk_bf16_f32 v120, v64, v65
	v_cvt_pk_bf16_f32 v121, v66, v67
	v_cvt_pk_bf16_f32 v122, v68, v69
	v_cvt_pk_bf16_f32 v123, v70, v71
	v_cvt_pk_bf16_f32 v124, v72, v73
	v_cvt_pk_bf16_f32 v125, v74, v75
	v_cvt_pk_bf16_f32 v126, v76, v77
	v_cvt_pk_bf16_f32 v127, v78, v79
	ds_read_b64_tr_b16 v[176:177], v242 offset:28672
	ds_read_b64_tr_b16 v[178:179], v242 offset:29184
	ds_read_b64_tr_b16 v[180:181], v242 offset:29696
	ds_read_b64_tr_b16 v[182:183], v242 offset:30208
	ds_read_b64_tr_b16 v[184:185], v242 offset:30720
	ds_read_b64_tr_b16 v[186:187], v242 offset:31232
	ds_read_b64_tr_b16 v[188:189], v242 offset:31744
	s_waitcnt lgkmcnt(14)
	ds_read_b64_tr_b16 v[190:191], v242 offset:32256
	s_waitcnt lgkmcnt(0)
	v_mfma_f32_32x32x16_bf16 v[0:15], v[160:163], v[112:115], v[0:15]
	v_mfma_f32_32x32x16_bf16 v[0:15], v[164:167], v[116:119], v[0:15]
	v_mfma_f32_32x32x16_bf16 v[0:15], v[168:171], v[120:123], v[0:15]
	v_mfma_f32_32x32x16_bf16 v[0:15], v[172:175], v[124:127], v[0:15]
	v_mfma_f32_32x32x16_bf16 v[16:31], v[176:179], v[112:115], v[16:31]
	v_mfma_f32_32x32x16_bf16 v[16:31], v[180:183], v[116:119], v[16:31]
	v_mfma_f32_32x32x16_bf16 v[16:31], v[184:187], v[120:123], v[16:31]
	v_mfma_f32_32x32x16_bf16 v[16:31], v[188:191], v[124:127], v[16:31]
	s_branch .Lg_done
.Lg_drainB:
	s_add_i32 s72, s7, 2
	s_mul_hi_u32 s80, s72, 0x55555556
	s_mul_i32 s80, s80, 3
	s_sub_u32 s80, s72, s80
	s_lshl_b32 s81, s80, 13
	s_cmp_eq_u32 s80, 2
	s_cselect_b32 s81, 0x6000, s81
	v_add_u32_e32 v242, s81, v253
	ds_read_b64_tr_b16 v[160:161], v242 offset:24576
	ds_read_b64_tr_b16 v[162:163], v242 offset:25088
	ds_read_b64_tr_b16 v[164:165], v242 offset:25600
	ds_read_b64_tr_b16 v[166:167], v242 offset:26112
	ds_read_b64_tr_b16 v[168:169], v242 offset:26624
	ds_read_b64_tr_b16 v[170:171], v242 offset:27136
	ds_read_b64_tr_b16 v[172:173], v242 offset:27648
	ds_read_b64_tr_b16 v[174:175], v242 offset:28160
	v_add_f32_e32 v204, v204, v80
	v_add_f32_e32 v205, v205, v81
	v_add_f32_e32 v208, v208, v82
	v_add_f32_e32 v209, v209, v83
	v_add_f32_e32 v204, v204, v84
	v_add_f32_e32 v205, v205, v85
	v_add_f32_e32 v208, v208, v86
	v_add_f32_e32 v209, v209, v87
	v_add_f32_e32 v204, v204, v88
	v_add_f32_e32 v205, v205, v89
	v_add_f32_e32 v208, v208, v90
	v_add_f32_e32 v209, v209, v91
	v_add_f32_e32 v204, v204, v92
	v_add_f32_e32 v205, v205, v93
	v_add_f32_e32 v208, v208, v94
	v_add_f32_e32 v209, v209, v95
	v_add_f32_e32 v204, v204, v48
	v_add_f32_e32 v205, v205, v49
	v_add_f32_e32 v208, v208, v50
	v_add_f32_e32 v209, v209, v51
	v_add_f32_e32 v204, v204, v52
	v_add_f32_e32 v205, v205, v53
	v_add_f32_e32 v208, v208, v54
	v_add_f32_e32 v209, v209, v55
	v_add_f32_e32 v204, v204, v56
	v_add_f32_e32 v205, v205, v57
	v_add_f32_e32 v208, v208, v58
	v_add_f32_e32 v209, v209, v59
	v_add_f32_e32 v204, v204, v60
	v_add_f32_e32 v205, v205, v61
	v_add_f32_e32 v208, v208, v62
	v_add_f32_e32 v209, v209, v63
	v_cvt_pk_bf16_f32 v112, v80, v81
	v_cvt_pk_bf16_f32 v113, v82, v83
	v_cvt_pk_bf16_f32 v114, v84, v85
	v_cvt_pk_bf16_f32 v115, v86, v87
	v_cvt_pk_bf16_f32 v116, v88, v89
	v_cvt_pk_bf16_f32 v117, v90, v91
	v_cvt_pk_bf16_f32 v118, v92, v93
	v_cvt_pk_bf16_f32 v119, v94, v95
	v_cvt_pk_bf16_f32 v120, v48, v49
	v_cvt_pk_bf16_f32 v121, v50, v51
	v_cvt_pk_bf16_f32 v122, v52, v53
	v_cvt_pk_bf16_f32 v123, v54, v55
	v_cvt_pk_bf16_f32 v124, v56, v57
	v_cvt_pk_bf16_f32 v125, v58, v59
	v_cvt_pk_bf16_f32 v126, v60, v61
	v_cvt_pk_bf16_f32 v127, v62, v63
	ds_read_b64_tr_b16 v[176:177], v242 offset:28672
	ds_read_b64_tr_b16 v[178:179], v242 offset:29184
	ds_read_b64_tr_b16 v[180:181], v242 offset:29696
	ds_read_b64_tr_b16 v[182:183], v242 offset:30208
	ds_read_b64_tr_b16 v[184:185], v242 offset:30720
	ds_read_b64_tr_b16 v[186:187], v242 offset:31232
	ds_read_b64_tr_b16 v[188:189], v242 offset:31744
	s_waitcnt lgkmcnt(14)
	ds_read_b64_tr_b16 v[190:191], v242 offset:32256
	s_waitcnt lgkmcnt(0)
	v_mfma_f32_32x32x16_bf16 v[0:15], v[160:163], v[112:115], v[0:15]
	v_mfma_f32_32x32x16_bf16 v[0:15], v[164:167], v[116:119], v[0:15]
	v_mfma_f32_32x32x16_bf16 v[0:15], v[168:171], v[120:123], v[0:15]
	v_mfma_f32_32x32x16_bf16 v[0:15], v[172:175], v[124:127], v[0:15]
	v_mfma_f32_32x32x16_bf16 v[16:31], v[176:179], v[112:115], v[16:31]
	v_mfma_f32_32x32x16_bf16 v[16:31], v[180:183], v[116:119], v[16:31]
	v_mfma_f32_32x32x16_bf16 v[16:31], v[184:187], v[120:123], v[16:31]
	v_mfma_f32_32x32x16_bf16 v[16:31], v[188:191], v[124:127], v[16:31]
.Lg_done:
	v_add_f32_e32 v204, v204, v205
	v_add_f32_e32 v208, v208, v209
	v_add_f32_e32 v124, v204, v208
	s_waitcnt lgkmcnt(0)
	s_barrier
	s_branch .LBB0_535
